# v143 + P4 epilogue: a lane's two sum-of-squares partials written as one 8-byte write-through store (slot order tn*4+wr*2+ai; halves the partial-sector hss stores)
# speedup vs baseline: 1.0041x; 1.0041x over previous
.LBB0_318:
	s_or_b64 exec, exec, s[46:47]
	v_and_b32_e32 v131, 64, v164
	v_xor_b32_e32 v130, 16, v164
	v_add_u32_e32 v131, 64, v131
	v_cmp_lt_i32_e32 vcc, v130, v131
	v_lshl_or_b32 v150, s16, 8, v1
	v_lshl_or_b32 v152, s38, 8, v147
	v_cndmask_b32_e32 v130, v164, v130, vcc
	v_lshlrev_b32_e32 v167, 2, v130
	v_xor_b32_e32 v130, 32, v164
	v_cmp_lt_i32_e32 vcc, v130, v131
	s_waitcnt vmcnt(0)
	s_barrier
	v_mbcnt_lo_u32_b32 v204, -1, 0
	v_mbcnt_hi_u32_b32 v204, -1, v204
	v_bfe_u32 v204, v204, 4, 1
	v_mul_u32_u24_e32 v204, 24, v204
	v_mov_b32_e32 v205, 0
	v_cndmask_b32_e32 v130, v164, v130, vcc
	v_lshlrev_b32_e32 v166, 2, v130
	v_ashrrev_i32_e32 v151, 31, v150
	s_lshl_b32 s46, s16, 2
	v_ashrrev_i32_e32 v153, 31, v152
	v_readlane_b32 s60, v249, 38
	v_lshlrev_b64 v[130:131], 12, v[152:153]
	v_readlane_b32 s61, v249, 39
	v_lshlrev_b64 v[154:155], 11, v[152:153]
	v_lshl_add_u64 v[154:155], s[12:13], 0, v[154:155]
	v_lshl_add_u64 v[130:131], s[60:61], 0, v[130:131]
	v_lshl_add_u64 v[130:131], v[150:151], 2, v[130:131]
	global_load_dwordx4 v[168:171], v[130:131], off
	global_load_dwordx4 v[172:175], v[130:131], off offset:64
	global_load_dwordx4 v[176:179], v[130:131], off offset:128
	global_load_dwordx4 v[180:183], v[130:131], off offset:192
	global_load_dwordx4 v[142:145], v[130:131], off offset:512
	global_load_dwordx4 v[138:141], v[130:131], off offset:576
	global_load_dwordx4 v[134:137], v[130:131], off offset:640
	s_nop 0
	global_load_dwordx4 v[130:133], v[130:131], off offset:704
	v_lshlrev_b64 v[184:185], 6, v[152:153]
	v_lshl_add_u64 v[154:155], v[150:151], 1, v[154:155]
	v_lshlrev_b32_e32 v148, 3, v146
	v_readlane_b32 s62, v249, 40
	v_readlane_b32 s63, v249, 41
	v_readlane_b32 s64, v249, 42
	v_readlane_b32 s65, v249, 43
	v_readlane_b32 s66, v249, 44
	v_readlane_b32 s67, v249, 45
	v_readlane_b32 s68, v249, 46
	v_readlane_b32 s69, v249, 47
	v_readlane_b32 s70, v249, 48
	v_readlane_b32 s71, v249, 49
	v_readlane_b32 s72, v249, 50
	v_readlane_b32 s73, v249, 51
	v_readlane_b32 s74, v249, 52
	v_readlane_b32 s75, v249, 53
	s_waitcnt vmcnt(7)
	v_pk_add_f32 v[118:119], v[118:119], v[168:169]
	v_pk_add_f32 v[120:121], v[120:121], v[170:171]
	s_waitcnt vmcnt(6)
	v_pk_add_f32 v[122:123], v[122:123], v[172:173]
	v_pk_add_f32 v[124:125], v[124:125], v[174:175]
	s_waitcnt vmcnt(5)
	v_pk_add_f32 v[126:127], v[126:127], v[176:177]
	s_waitcnt vmcnt(4)
	v_pk_add_f32 v[168:169], v[116:117], v[182:183]
	v_pk_mul_f32 v[116:117], v[118:119], v[118:119]
	v_pk_mul_f32 v[170:171], v[120:121], v[120:121]
	v_cvt_pk_bf16_f32 v186, v118, v119
	v_cvt_pk_bf16_f32 v187, v120, v121
	v_pk_mul_f32 v[120:121], v[122:123], v[122:123]
	v_pk_add_f32 v[128:129], v[128:129], v[178:179]
	v_pk_add_f32 v[114:115], v[114:115], v[180:181]
	v_pk_mul_f32 v[172:173], v[124:125], v[124:125]
	v_cvt_pk_bf16_f32 v188, v122, v123
	v_cvt_pk_bf16_f32 v189, v124, v125
	v_pk_mul_f32 v[124:125], v[126:127], v[126:127]
	v_add_f32_e32 v120, v120, v121
	v_add_f32_e32 v116, v116, v117
	v_pk_mul_f32 v[174:175], v[128:129], v[128:129]
	v_cvt_pk_bf16_f32 v190, v126, v127
	v_cvt_pk_bf16_f32 v191, v128, v129
	v_pk_mul_f32 v[128:129], v[114:115], v[114:115]
	v_add_f32_e32 v117, v124, v125
	v_add_f32_e32 v120, v120, v172
	v_add_f32_e32 v116, v116, v170
	v_pk_mul_f32 v[176:177], v[168:169], v[168:169]
	v_add_f32_e32 v121, v128, v129
	v_add_f32_e32 v117, v117, v174
	v_add_f32_e32 v120, v120, v173
	v_add_f32_e32 v116, v116, v171
	v_add_f32_e32 v121, v121, v176
	v_add_f32_e32 v117, v117, v175
	v_add_f32_e32 v116, v116, v120
	v_add_f32_e32 v116, v116, v117
	v_add_f32_e32 v117, v121, v177
	v_add_f32_e32 v116, v116, v117
	ds_bpermute_b32 v117, v167, v116
	v_cvt_pk_bf16_f32 v192, v114, v115
	v_cvt_pk_bf16_f32 v193, v168, v169
	s_nop 1
	v_permlane16_swap_b32_e32 v186, v188
	v_permlane16_swap_b32_e32 v187, v189
	v_permlane16_swap_b32_e32 v190, v192
	v_permlane16_swap_b32_e32 v191, v193
	v_lshl_add_u64 v[202:203], v[154:155], 0, v[204:205]
	global_store_dwordx4 v[202:203], v[186:189], off sc1
	global_store_dwordx4 v[202:203], v[190:193], off offset:64 sc1
	s_waitcnt lgkmcnt(0)
	v_add_f32_e32 v116, v116, v117
	ds_bpermute_b32 v117, v166, v116
	v_lshl_add_u64 v[114:115], s[90:91], 0, v[184:185]
	s_and_saveexec_b64 s[38:39], s[8:9]
	s_cbranch_execz .LBB0_320
	s_lshl_b32 s16, s46, 2
	s_waitcnt lgkmcnt(0)
	v_add_f32_e32 v246, v116, v117
.LBB0_320:
	s_or_b64 exec, exec, s[38:39]
	s_waitcnt vmcnt(5)
	v_pk_add_f32 v[110:111], v[110:111], v[142:143]
	v_pk_add_f32 v[112:113], v[112:113], v[144:145]
	s_waitcnt lgkmcnt(0)
	v_pk_mul_f32 v[116:117], v[110:111], v[110:111]
	v_cvt_pk_bf16_f32 v194, v110, v111
	v_cvt_pk_bf16_f32 v195, v112, v113
	s_waitcnt vmcnt(4)
	v_pk_add_f32 v[106:107], v[106:107], v[138:139]
	v_pk_add_f32 v[108:109], v[108:109], v[140:141]
	v_pk_mul_f32 v[110:111], v[106:107], v[106:107]
	v_pk_mul_f32 v[118:119], v[112:113], v[112:113]
	v_pk_mul_f32 v[112:113], v[108:109], v[108:109]
	v_cvt_pk_bf16_f32 v196, v106, v107
	v_add_f32_e32 v107, v110, v111
	v_add_f32_e32 v110, v116, v117
	s_waitcnt vmcnt(3)
	v_pk_add_f32 v[102:103], v[102:103], v[134:135]
	v_add_f32_e32 v107, v107, v112
	v_add_f32_e32 v110, v110, v118
	v_pk_add_f32 v[104:105], v[104:105], v[136:137]
	v_pk_mul_f32 v[120:121], v[102:103], v[102:103]
	s_waitcnt vmcnt(2)
	v_pk_add_f32 v[124:125], v[98:99], v[130:131]
	v_add_f32_e32 v107, v107, v113
	v_add_f32_e32 v110, v110, v119
	v_pk_mul_f32 v[122:123], v[104:105], v[104:105]
	v_pk_add_f32 v[100:101], v[100:101], v[132:133]
	v_pk_mul_f32 v[98:99], v[124:125], v[124:125]
	v_add_f32_e32 v107, v110, v107
	v_add_f32_e32 v110, v120, v121
	v_pk_mul_f32 v[126:127], v[100:101], v[100:101]
	v_add_f32_e32 v110, v110, v122
	v_add_f32_e32 v98, v98, v99
	v_add_f32_e32 v110, v110, v123
	v_add_f32_e32 v98, v98, v126
	v_add_f32_e32 v107, v107, v110
	v_add_f32_e32 v98, v98, v127
	v_add_f32_e32 v98, v107, v98
	ds_bpermute_b32 v99, v167, v98
	v_cvt_pk_bf16_f32 v197, v108, v109
	v_cvt_pk_bf16_f32 v198, v102, v103
	v_cvt_pk_bf16_f32 v199, v104, v105
	s_waitcnt lgkmcnt(0)
	v_add_f32_e32 v98, v98, v99
	ds_bpermute_b32 v99, v166, v98
	v_cvt_pk_bf16_f32 v200, v124, v125
	v_cvt_pk_bf16_f32 v201, v100, v101
	s_nop 1
	v_permlane16_swap_b32_e32 v194, v196
	v_permlane16_swap_b32_e32 v195, v197
	v_permlane16_swap_b32_e32 v198, v200
	v_permlane16_swap_b32_e32 v199, v201
	v_lshl_add_u64 v[202:203], v[154:155], 0, v[204:205]
	global_store_dwordx4 v[202:203], v[194:197], off offset:256 sc1
	global_store_dwordx4 v[202:203], v[198:201], off offset:320 sc1
	s_and_saveexec_b64 s[38:39], s[8:9]
	s_cbranch_execz .LBB0_322
	s_lshl_b32 s16, s46, 2
	s_waitcnt lgkmcnt(0)
	v_add_f32_e32 v247, v98, v99
	v_lshl_add_u64 v[98:99], v[114:115], 0, s[16:17]
	v_lshl_add_u64 v[98:99], v[98:99], 0, v[148:149]
	global_store_dwordx2 v[98:99], v[246:247], off sc1
.LBB0_322:
	s_or_b64 exec, exec, s[38:39]
	v_add_u32_e32 v114, 16, v152
	v_ashrrev_i32_e32 v115, 31, v114
	v_readlane_b32 s60, v249, 38
	s_waitcnt lgkmcnt(0)
	v_lshlrev_b64 v[98:99], 12, v[114:115]
	v_readlane_b32 s61, v249, 39
	v_lshlrev_b64 v[132:133], 11, v[114:115]
	v_lshlrev_b64 v[134:135], 6, v[114:115]
	v_lshl_add_u64 v[98:99], s[60:61], 0, v[98:99]
	v_lshl_add_u64 v[98:99], v[150:151], 2, v[98:99]
	global_load_dwordx4 v[116:119], v[98:99], off
	global_load_dwordx4 v[120:123], v[98:99], off offset:64
	global_load_dwordx4 v[124:127], v[98:99], off offset:128
	global_load_dwordx4 v[128:131], v[98:99], off offset:192
	global_load_dwordx4 v[110:113], v[98:99], off offset:512
	global_load_dwordx4 v[106:109], v[98:99], off offset:576
	global_load_dwordx4 v[102:105], v[98:99], off offset:640
	s_nop 0
	global_load_dwordx4 v[98:101], v[98:99], off offset:704
	v_lshl_add_u64 v[114:115], s[12:13], 0, v[132:133]
	v_lshl_add_u64 v[114:115], v[150:151], 1, v[114:115]
	v_readlane_b32 s62, v249, 40
	v_readlane_b32 s63, v249, 41
	v_readlane_b32 s64, v249, 42
	v_readlane_b32 s65, v249, 43
	v_readlane_b32 s66, v249, 44
	v_readlane_b32 s67, v249, 45
	v_readlane_b32 s68, v249, 46
	v_readlane_b32 s69, v249, 47
	v_readlane_b32 s70, v249, 48
	v_readlane_b32 s71, v249, 49
	v_readlane_b32 s72, v249, 50
	v_readlane_b32 s73, v249, 51
	v_readlane_b32 s74, v249, 52
	v_readlane_b32 s75, v249, 53
	s_waitcnt vmcnt(7)
	v_pk_add_f32 v[86:87], v[86:87], v[116:117]
	v_pk_add_f32 v[88:89], v[88:89], v[118:119]
	s_waitcnt vmcnt(6)
	v_pk_add_f32 v[90:91], v[90:91], v[120:121]
	v_pk_add_f32 v[92:93], v[92:93], v[122:123]
	s_waitcnt vmcnt(5)
	v_pk_add_f32 v[94:95], v[94:95], v[124:125]
	s_waitcnt vmcnt(4)
	v_pk_add_f32 v[116:117], v[84:85], v[130:131]
	v_pk_mul_f32 v[84:85], v[86:87], v[86:87]
	v_pk_mul_f32 v[118:119], v[88:89], v[88:89]
	v_cvt_pk_bf16_f32 v186, v86, v87
	v_cvt_pk_bf16_f32 v187, v88, v89
	v_pk_mul_f32 v[88:89], v[90:91], v[90:91]
	v_pk_add_f32 v[96:97], v[96:97], v[126:127]
	v_pk_add_f32 v[82:83], v[82:83], v[128:129]
	v_pk_mul_f32 v[120:121], v[92:93], v[92:93]
	v_cvt_pk_bf16_f32 v188, v90, v91
	v_cvt_pk_bf16_f32 v189, v92, v93
	v_pk_mul_f32 v[92:93], v[94:95], v[94:95]
	v_add_f32_e32 v88, v88, v89
	v_add_f32_e32 v84, v84, v85
	v_pk_mul_f32 v[122:123], v[96:97], v[96:97]
	v_pk_mul_f32 v[124:125], v[82:83], v[82:83]
	v_add_f32_e32 v85, v92, v93
	v_add_f32_e32 v88, v88, v120
	v_add_f32_e32 v84, v84, v118
	v_pk_mul_f32 v[126:127], v[116:117], v[116:117]
	v_add_f32_e32 v89, v124, v125
	v_add_f32_e32 v85, v85, v122
	v_add_f32_e32 v88, v88, v121
	v_add_f32_e32 v84, v84, v119
	v_add_f32_e32 v89, v89, v126
	v_add_f32_e32 v85, v85, v123
	v_add_f32_e32 v84, v84, v88
	v_add_f32_e32 v84, v84, v85
	v_add_f32_e32 v85, v89, v127
	v_add_f32_e32 v84, v84, v85
	ds_bpermute_b32 v85, v167, v84
	v_cvt_pk_bf16_f32 v192, v82, v83
	v_cvt_pk_bf16_f32 v193, v116, v117
	v_cvt_pk_bf16_f32 v190, v94, v95
	v_cvt_pk_bf16_f32 v191, v96, v97
	s_waitcnt lgkmcnt(0)
	v_add_f32_e32 v84, v84, v85
	ds_bpermute_b32 v85, v166, v84
	s_nop 1
	v_permlane16_swap_b32_e32 v186, v188
	v_permlane16_swap_b32_e32 v187, v189
	v_permlane16_swap_b32_e32 v190, v192
	v_permlane16_swap_b32_e32 v191, v193
	v_lshl_add_u64 v[202:203], v[114:115], 0, v[204:205]
	global_store_dwordx4 v[202:203], v[186:189], off sc1
	global_store_dwordx4 v[202:203], v[190:193], off offset:64 sc1
	v_lshl_add_u64 v[82:83], s[90:91], 0, v[134:135]
	s_and_saveexec_b64 s[38:39], s[8:9]
	s_cbranch_execz .LBB0_324
	s_lshl_b32 s16, s46, 2
	s_waitcnt lgkmcnt(0)
	v_add_f32_e32 v246, v84, v85
.LBB0_324:
	s_or_b64 exec, exec, s[38:39]
	s_waitcnt vmcnt(5)
	v_pk_add_f32 v[78:79], v[78:79], v[110:111]
	v_pk_add_f32 v[80:81], v[80:81], v[112:113]
	s_waitcnt lgkmcnt(0)
	v_pk_mul_f32 v[84:85], v[78:79], v[78:79]
	v_cvt_pk_bf16_f32 v194, v78, v79
	v_cvt_pk_bf16_f32 v195, v80, v81
	s_waitcnt vmcnt(4)
	v_pk_add_f32 v[74:75], v[74:75], v[106:107]
	v_pk_add_f32 v[76:77], v[76:77], v[108:109]
	v_pk_mul_f32 v[78:79], v[74:75], v[74:75]
	v_pk_mul_f32 v[86:87], v[80:81], v[80:81]
	v_pk_mul_f32 v[80:81], v[76:77], v[76:77]
	v_cvt_pk_bf16_f32 v196, v74, v75
	v_add_f32_e32 v75, v78, v79
	v_add_f32_e32 v78, v84, v85
	s_waitcnt vmcnt(3)
	v_pk_add_f32 v[70:71], v[70:71], v[102:103]
	v_add_f32_e32 v75, v75, v80
	v_add_f32_e32 v78, v78, v86
	v_pk_add_f32 v[72:73], v[72:73], v[104:105]
	v_pk_mul_f32 v[88:89], v[70:71], v[70:71]
	s_waitcnt vmcnt(2)
	v_pk_add_f32 v[92:93], v[66:67], v[98:99]
	v_add_f32_e32 v75, v75, v81
	v_add_f32_e32 v78, v78, v87
	v_pk_mul_f32 v[90:91], v[72:73], v[72:73]
	v_pk_add_f32 v[68:69], v[68:69], v[100:101]
	v_pk_mul_f32 v[66:67], v[92:93], v[92:93]
	v_add_f32_e32 v75, v78, v75
	v_add_f32_e32 v78, v88, v89
	v_pk_mul_f32 v[94:95], v[68:69], v[68:69]
	v_add_f32_e32 v78, v78, v90
	v_add_f32_e32 v66, v66, v67
	v_add_f32_e32 v78, v78, v91
	v_add_f32_e32 v66, v66, v94
	v_add_f32_e32 v75, v75, v78
	v_add_f32_e32 v66, v66, v95
	v_add_f32_e32 v66, v75, v66
	ds_bpermute_b32 v67, v167, v66
	v_cvt_pk_bf16_f32 v197, v76, v77
	v_cvt_pk_bf16_f32 v198, v70, v71
	v_cvt_pk_bf16_f32 v199, v72, v73
	s_waitcnt lgkmcnt(0)
	v_add_f32_e32 v66, v66, v67
	ds_bpermute_b32 v67, v166, v66
	v_cvt_pk_bf16_f32 v200, v92, v93
	v_cvt_pk_bf16_f32 v201, v68, v69
	s_nop 1
	v_permlane16_swap_b32_e32 v194, v196
	v_permlane16_swap_b32_e32 v195, v197
	v_permlane16_swap_b32_e32 v198, v200
	v_permlane16_swap_b32_e32 v199, v201
	v_lshl_add_u64 v[202:203], v[114:115], 0, v[204:205]
	global_store_dwordx4 v[202:203], v[194:197], off offset:256 sc1
	global_store_dwordx4 v[202:203], v[198:201], off offset:320 sc1
	s_and_saveexec_b64 s[38:39], s[8:9]
	s_cbranch_execz .LBB0_326
	s_lshl_b32 s16, s46, 2
	s_waitcnt lgkmcnt(0)
	v_add_f32_e32 v247, v66, v67
	v_lshl_add_u64 v[66:67], v[82:83], 0, s[16:17]
	v_lshl_add_u64 v[66:67], v[66:67], 0, v[148:149]
	global_store_dwordx2 v[66:67], v[246:247], off sc1
.LBB0_326:
	s_or_b64 exec, exec, s[38:39]
	v_add_u32_e32 v82, 0x80, v152
	v_ashrrev_i32_e32 v83, 31, v82
	v_readlane_b32 s60, v249, 38
	s_waitcnt lgkmcnt(0)
	v_lshlrev_b64 v[66:67], 12, v[82:83]
	v_readlane_b32 s61, v249, 39
	v_lshlrev_b64 v[100:101], 11, v[82:83]
	v_lshlrev_b64 v[102:103], 6, v[82:83]
	v_lshl_add_u64 v[66:67], s[60:61], 0, v[66:67]
	v_lshl_add_u64 v[66:67], v[150:151], 2, v[66:67]
	global_load_dwordx4 v[84:87], v[66:67], off
	global_load_dwordx4 v[88:91], v[66:67], off offset:64
	global_load_dwordx4 v[92:95], v[66:67], off offset:128
	global_load_dwordx4 v[96:99], v[66:67], off offset:192
	global_load_dwordx4 v[78:81], v[66:67], off offset:512
	global_load_dwordx4 v[74:77], v[66:67], off offset:576
	global_load_dwordx4 v[70:73], v[66:67], off offset:640
	s_nop 0
	global_load_dwordx4 v[66:69], v[66:67], off offset:704
	v_lshl_add_u64 v[82:83], s[12:13], 0, v[100:101]
	v_lshl_add_u64 v[82:83], v[150:151], 1, v[82:83]
	v_readlane_b32 s62, v249, 40
	v_readlane_b32 s63, v249, 41
	v_readlane_b32 s64, v249, 42
	v_readlane_b32 s65, v249, 43
	v_readlane_b32 s66, v249, 44
	v_readlane_b32 s67, v249, 45
	v_readlane_b32 s68, v249, 46
	v_readlane_b32 s69, v249, 47
	v_readlane_b32 s70, v249, 48
	v_readlane_b32 s71, v249, 49
	v_readlane_b32 s72, v249, 50
	v_readlane_b32 s73, v249, 51
	v_readlane_b32 s74, v249, 52
	v_readlane_b32 s75, v249, 53
	s_waitcnt vmcnt(7)
	v_pk_add_f32 v[54:55], v[54:55], v[84:85]
	v_pk_add_f32 v[56:57], v[56:57], v[86:87]
	s_waitcnt vmcnt(6)
	v_pk_add_f32 v[58:59], v[58:59], v[88:89]
	v_pk_add_f32 v[60:61], v[60:61], v[90:91]
	s_waitcnt vmcnt(5)
	v_pk_add_f32 v[62:63], v[62:63], v[92:93]
	s_waitcnt vmcnt(4)
	v_pk_add_f32 v[84:85], v[52:53], v[98:99]
	v_pk_mul_f32 v[52:53], v[54:55], v[54:55]
	v_pk_mul_f32 v[86:87], v[56:57], v[56:57]
	v_cvt_pk_bf16_f32 v186, v54, v55
	v_cvt_pk_bf16_f32 v187, v56, v57
	v_pk_mul_f32 v[56:57], v[58:59], v[58:59]
	v_pk_add_f32 v[64:65], v[64:65], v[94:95]
	v_pk_add_f32 v[50:51], v[50:51], v[96:97]
	v_pk_mul_f32 v[88:89], v[60:61], v[60:61]
	v_cvt_pk_bf16_f32 v188, v58, v59
	v_cvt_pk_bf16_f32 v189, v60, v61
	v_pk_mul_f32 v[60:61], v[62:63], v[62:63]
	v_add_f32_e32 v56, v56, v57
	v_add_f32_e32 v52, v52, v53
	v_pk_mul_f32 v[90:91], v[64:65], v[64:65]
	v_pk_mul_f32 v[92:93], v[50:51], v[50:51]
	v_add_f32_e32 v53, v60, v61
	v_add_f32_e32 v56, v56, v88
	v_add_f32_e32 v52, v52, v86
	v_pk_mul_f32 v[94:95], v[84:85], v[84:85]
	v_add_f32_e32 v57, v92, v93
	v_add_f32_e32 v53, v53, v90
	v_add_f32_e32 v56, v56, v89
	v_add_f32_e32 v52, v52, v87
	v_add_f32_e32 v57, v57, v94
	v_add_f32_e32 v53, v53, v91
	v_add_f32_e32 v52, v52, v56
	v_add_f32_e32 v52, v52, v53
	v_add_f32_e32 v53, v57, v95
	v_add_f32_e32 v52, v52, v53
	ds_bpermute_b32 v53, v167, v52
	v_cvt_pk_bf16_f32 v192, v50, v51
	v_cvt_pk_bf16_f32 v193, v84, v85
	v_cvt_pk_bf16_f32 v190, v62, v63
	v_cvt_pk_bf16_f32 v191, v64, v65
	s_waitcnt lgkmcnt(0)
	v_add_f32_e32 v52, v52, v53
	ds_bpermute_b32 v53, v166, v52
	s_nop 1
	v_permlane16_swap_b32_e32 v186, v188
	v_permlane16_swap_b32_e32 v187, v189
	v_permlane16_swap_b32_e32 v190, v192
	v_permlane16_swap_b32_e32 v191, v193
	v_lshl_add_u64 v[202:203], v[82:83], 0, v[204:205]
	global_store_dwordx4 v[202:203], v[186:189], off sc1
	global_store_dwordx4 v[202:203], v[190:193], off offset:64 sc1
	v_lshl_add_u64 v[50:51], s[90:91], 0, v[102:103]
	s_and_saveexec_b64 s[38:39], s[8:9]
	s_cbranch_execz .LBB0_328
	s_lshl_b32 s16, s46, 2
	s_waitcnt lgkmcnt(0)
	v_add_f32_e32 v246, v52, v53
.LBB0_328:
	s_or_b64 exec, exec, s[38:39]
	s_waitcnt vmcnt(5)
	v_pk_add_f32 v[46:47], v[46:47], v[78:79]
	v_pk_add_f32 v[48:49], v[48:49], v[80:81]
	s_waitcnt lgkmcnt(0)
	v_pk_mul_f32 v[52:53], v[46:47], v[46:47]
	v_cvt_pk_bf16_f32 v194, v46, v47
	v_cvt_pk_bf16_f32 v195, v48, v49
	s_waitcnt vmcnt(4)
	v_pk_add_f32 v[42:43], v[42:43], v[74:75]
	v_pk_add_f32 v[44:45], v[44:45], v[76:77]
	v_pk_mul_f32 v[46:47], v[42:43], v[42:43]
	v_pk_mul_f32 v[54:55], v[48:49], v[48:49]
	v_pk_mul_f32 v[48:49], v[44:45], v[44:45]
	v_cvt_pk_bf16_f32 v196, v42, v43
	v_add_f32_e32 v43, v46, v47
	v_add_f32_e32 v46, v52, v53
	s_waitcnt vmcnt(3)
	v_pk_add_f32 v[38:39], v[38:39], v[70:71]
	v_add_f32_e32 v43, v43, v48
	v_add_f32_e32 v46, v46, v54
	v_pk_add_f32 v[40:41], v[40:41], v[72:73]
	v_pk_mul_f32 v[56:57], v[38:39], v[38:39]
	s_waitcnt vmcnt(2)
	v_pk_add_f32 v[60:61], v[34:35], v[66:67]
	v_add_f32_e32 v43, v43, v49
	v_add_f32_e32 v46, v46, v55
	v_pk_mul_f32 v[58:59], v[40:41], v[40:41]
	v_pk_add_f32 v[36:37], v[36:37], v[68:69]
	v_pk_mul_f32 v[34:35], v[60:61], v[60:61]
	v_add_f32_e32 v43, v46, v43
	v_add_f32_e32 v46, v56, v57
	v_pk_mul_f32 v[62:63], v[36:37], v[36:37]
	v_add_f32_e32 v46, v46, v58
	v_add_f32_e32 v34, v34, v35
	v_add_f32_e32 v46, v46, v59
	v_add_f32_e32 v34, v34, v62
	v_add_f32_e32 v43, v43, v46
	v_add_f32_e32 v34, v34, v63
	v_add_f32_e32 v34, v43, v34
	ds_bpermute_b32 v35, v167, v34
	v_cvt_pk_bf16_f32 v197, v44, v45
	v_cvt_pk_bf16_f32 v198, v38, v39
	v_cvt_pk_bf16_f32 v199, v40, v41
	s_waitcnt lgkmcnt(0)
	v_add_f32_e32 v34, v34, v35
	ds_bpermute_b32 v35, v166, v34
	v_cvt_pk_bf16_f32 v200, v60, v61
	v_cvt_pk_bf16_f32 v201, v36, v37
	s_nop 1
	v_permlane16_swap_b32_e32 v194, v196
	v_permlane16_swap_b32_e32 v195, v197
	v_permlane16_swap_b32_e32 v198, v200
	v_permlane16_swap_b32_e32 v199, v201
	v_lshl_add_u64 v[202:203], v[82:83], 0, v[204:205]
	global_store_dwordx4 v[202:203], v[194:197], off offset:256 sc1
	global_store_dwordx4 v[202:203], v[198:201], off offset:320 sc1
	s_and_saveexec_b64 s[38:39], s[8:9]
	s_cbranch_execz .LBB0_330
	s_lshl_b32 s16, s46, 2
	s_waitcnt lgkmcnt(0)
	v_add_f32_e32 v247, v34, v35
	v_lshl_add_u64 v[34:35], v[50:51], 0, s[16:17]
	v_lshl_add_u64 v[34:35], v[34:35], 0, v[148:149]
	global_store_dwordx2 v[34:35], v[246:247], off sc1
.LBB0_330:
	s_or_b64 exec, exec, s[38:39]
	v_add_u32_e32 v50, 0x90, v152
	v_ashrrev_i32_e32 v51, 31, v50
	v_readlane_b32 s60, v249, 38
	s_waitcnt lgkmcnt(0)
	v_lshlrev_b64 v[34:35], 12, v[50:51]
	v_readlane_b32 s61, v249, 39
	v_lshlrev_b64 v[68:69], 11, v[50:51]
	v_lshlrev_b64 v[70:71], 6, v[50:51]
	v_lshl_add_u64 v[34:35], s[60:61], 0, v[34:35]
	v_lshl_add_u64 v[34:35], v[150:151], 2, v[34:35]
	global_load_dwordx4 v[52:55], v[34:35], off
	global_load_dwordx4 v[56:59], v[34:35], off offset:64
	global_load_dwordx4 v[60:63], v[34:35], off offset:128
	global_load_dwordx4 v[64:67], v[34:35], off offset:192
	global_load_dwordx4 v[46:49], v[34:35], off offset:512
	global_load_dwordx4 v[42:45], v[34:35], off offset:576
	global_load_dwordx4 v[38:41], v[34:35], off offset:640
	s_nop 0
	global_load_dwordx4 v[34:37], v[34:35], off offset:704
	v_lshl_add_u64 v[50:51], s[12:13], 0, v[68:69]
	v_lshl_add_u64 v[50:51], v[150:151], 1, v[50:51]
	v_readlane_b32 s62, v249, 40
	v_readlane_b32 s63, v249, 41
	v_readlane_b32 s64, v249, 42
	v_readlane_b32 s65, v249, 43
	v_readlane_b32 s66, v249, 44
	v_readlane_b32 s67, v249, 45
	v_readlane_b32 s68, v249, 46
	v_readlane_b32 s69, v249, 47
	v_readlane_b32 s70, v249, 48
	v_readlane_b32 s71, v249, 49
	v_readlane_b32 s72, v249, 50
	v_readlane_b32 s73, v249, 51
	v_readlane_b32 s74, v249, 52
	v_readlane_b32 s75, v249, 53
	s_waitcnt vmcnt(7)
	v_pk_add_f32 v[22:23], v[22:23], v[52:53]
	v_pk_add_f32 v[24:25], v[24:25], v[54:55]
	s_waitcnt vmcnt(6)
	v_pk_add_f32 v[26:27], v[26:27], v[56:57]
	v_pk_add_f32 v[28:29], v[28:29], v[58:59]
	s_waitcnt vmcnt(5)
	v_pk_add_f32 v[30:31], v[30:31], v[60:61]
	s_waitcnt vmcnt(4)
	v_pk_add_f32 v[52:53], v[20:21], v[66:67]
	v_pk_mul_f32 v[20:21], v[22:23], v[22:23]
	v_pk_mul_f32 v[54:55], v[24:25], v[24:25]
	v_cvt_pk_bf16_f32 v186, v22, v23
	v_cvt_pk_bf16_f32 v187, v24, v25
	v_pk_mul_f32 v[24:25], v[26:27], v[26:27]
	v_pk_add_f32 v[32:33], v[32:33], v[62:63]
	v_pk_add_f32 v[18:19], v[18:19], v[64:65]
	v_pk_mul_f32 v[56:57], v[28:29], v[28:29]
	v_cvt_pk_bf16_f32 v188, v26, v27
	v_cvt_pk_bf16_f32 v189, v28, v29
	v_pk_mul_f32 v[28:29], v[30:31], v[30:31]
	v_add_f32_e32 v24, v24, v25
	v_add_f32_e32 v20, v20, v21
	v_pk_mul_f32 v[58:59], v[32:33], v[32:33]
	v_pk_mul_f32 v[60:61], v[18:19], v[18:19]
	v_add_f32_e32 v21, v28, v29
	v_add_f32_e32 v24, v24, v56
	v_add_f32_e32 v20, v20, v54
	v_pk_mul_f32 v[62:63], v[52:53], v[52:53]
	v_add_f32_e32 v25, v60, v61
	v_add_f32_e32 v21, v21, v58
	v_add_f32_e32 v24, v24, v57
	v_add_f32_e32 v20, v20, v55
	v_add_f32_e32 v25, v25, v62
	v_add_f32_e32 v21, v21, v59
	v_add_f32_e32 v20, v20, v24
	v_add_f32_e32 v20, v20, v21
	v_add_f32_e32 v21, v25, v63
	v_add_f32_e32 v20, v20, v21
	ds_bpermute_b32 v21, v167, v20
	v_cvt_pk_bf16_f32 v192, v18, v19
	v_cvt_pk_bf16_f32 v193, v52, v53
	v_cvt_pk_bf16_f32 v190, v30, v31
	v_cvt_pk_bf16_f32 v191, v32, v33
	s_waitcnt lgkmcnt(0)
	v_add_f32_e32 v20, v20, v21
	ds_bpermute_b32 v21, v166, v20
	s_nop 1
	v_permlane16_swap_b32_e32 v186, v188
	v_permlane16_swap_b32_e32 v187, v189
	v_permlane16_swap_b32_e32 v190, v192
	v_permlane16_swap_b32_e32 v191, v193
	v_lshl_add_u64 v[202:203], v[50:51], 0, v[204:205]
	global_store_dwordx4 v[202:203], v[186:189], off sc1
	global_store_dwordx4 v[202:203], v[190:193], off offset:64 sc1
	v_lshl_add_u64 v[18:19], s[90:91], 0, v[70:71]
	s_and_saveexec_b64 s[38:39], s[8:9]
	s_cbranch_execz .LBB0_332
	s_lshl_b32 s16, s46, 2
	s_waitcnt lgkmcnt(0)
	v_add_f32_e32 v246, v20, v21
.LBB0_332:
	s_or_b64 exec, exec, s[38:39]
	s_waitcnt vmcnt(5)
	v_pk_add_f32 v[14:15], v[14:15], v[46:47]
	v_pk_add_f32 v[16:17], v[16:17], v[48:49]
	s_waitcnt lgkmcnt(0)
	v_pk_mul_f32 v[20:21], v[14:15], v[14:15]
	v_cvt_pk_bf16_f32 v194, v14, v15
	v_cvt_pk_bf16_f32 v195, v16, v17
	s_waitcnt vmcnt(4)
	v_pk_add_f32 v[10:11], v[10:11], v[42:43]
	v_pk_add_f32 v[12:13], v[12:13], v[44:45]
	v_pk_mul_f32 v[14:15], v[10:11], v[10:11]
	v_pk_mul_f32 v[22:23], v[16:17], v[16:17]
	v_pk_mul_f32 v[16:17], v[12:13], v[12:13]
	v_cvt_pk_bf16_f32 v196, v10, v11
	v_add_f32_e32 v11, v14, v15
	v_add_f32_e32 v14, v20, v21
	s_waitcnt vmcnt(3)
	v_pk_add_f32 v[6:7], v[6:7], v[38:39]
	v_add_f32_e32 v11, v11, v16
	v_add_f32_e32 v14, v14, v22
	v_pk_add_f32 v[8:9], v[8:9], v[40:41]
	v_pk_mul_f32 v[24:25], v[6:7], v[6:7]
	s_waitcnt vmcnt(2)
	v_pk_add_f32 v[28:29], v[2:3], v[34:35]
	v_add_f32_e32 v11, v11, v17
	v_add_f32_e32 v14, v14, v23
	v_pk_mul_f32 v[26:27], v[8:9], v[8:9]
	v_pk_add_f32 v[4:5], v[4:5], v[36:37]
	v_pk_mul_f32 v[2:3], v[28:29], v[28:29]
	v_add_f32_e32 v11, v14, v11
	v_add_f32_e32 v14, v24, v25
	v_pk_mul_f32 v[30:31], v[4:5], v[4:5]
	v_add_f32_e32 v14, v14, v26
	v_add_f32_e32 v2, v2, v3
	v_add_f32_e32 v14, v14, v27
	v_add_f32_e32 v2, v2, v30
	v_add_f32_e32 v11, v11, v14
	v_add_f32_e32 v2, v2, v31
	v_add_f32_e32 v2, v11, v2
	ds_bpermute_b32 v3, v167, v2
	v_cvt_pk_bf16_f32 v197, v12, v13
	v_cvt_pk_bf16_f32 v198, v6, v7
	v_cvt_pk_bf16_f32 v199, v8, v9
	s_waitcnt lgkmcnt(0)
	v_add_f32_e32 v2, v2, v3
	ds_bpermute_b32 v3, v166, v2
	v_cvt_pk_bf16_f32 v200, v28, v29
	v_cvt_pk_bf16_f32 v201, v4, v5
	s_nop 1
	v_permlane16_swap_b32_e32 v194, v196
	v_permlane16_swap_b32_e32 v195, v197
	v_permlane16_swap_b32_e32 v198, v200
	v_permlane16_swap_b32_e32 v199, v201
	v_lshl_add_u64 v[202:203], v[50:51], 0, v[204:205]
	global_store_dwordx4 v[202:203], v[194:197], off offset:256 sc1
	global_store_dwordx4 v[202:203], v[198:201], off offset:320 sc1
	s_and_saveexec_b64 s[38:39], s[8:9]
	s_cbranch_execz .LBB0_334
	s_lshl_b32 s16, s46, 2
	s_waitcnt lgkmcnt(0)
	v_add_f32_e32 v247, v2, v3
	v_lshl_add_u64 v[2:3], v[18:19], 0, s[16:17]
	v_lshl_add_u64 v[2:3], v[2:3], 0, v[148:149]
	global_store_dwordx2 v[2:3], v[246:247], off sc1
